# MoBA unit: cache prefetch of both query rows before the ksum/gating prologue
# speedup vs baseline: 1.0005x; 1.0005x over previous
.LBB0_879:
	s_and_b64 s[6:7], s[4:5], exec
	s_cselect_b32 s52, s88, s8
	v_mov_b32_e32 v10, v170
	s_lshl_b32 s7, s52, 7
	v_cmp_gt_i32_e32 vcc, s7, v170
	v_readfirstlane_b32 s6, v10
	s_ashr_i32 s9, s6, 1
	s_and_b32 s9, s9, 0xffffffe0
	s_lshl_b32 s36, s52, 8
	s_add_i32 s9, s9, s36
	v_and_b32_e32 v226, 15, v10
	v_or_b32_e32 v226, s9, v226
	v_mov_b64_e32 v[228:229], s[30:31]
	v_mad_i64_i32 v[228:229], s[36:37], v226, s65, v[228:229]
	s_mov_b32 s36, 0x30000
	s_mov_b32 s37, 0
	global_load_dword v230, v[228:229], off offset:-32
	global_load_dword v231, v[228:229], off offset:96
	v_lshl_add_u64 v[228:229], v[228:229], 0, s[36:37]
	global_load_dword v232, v[228:229], off offset:-32
	global_load_dword v233, v[228:229], off offset:96
	s_and_saveexec_b64 s[34:35], vcc
	s_cbranch_execz .LBB0_889
	v_max_i32_e32 v0, s7, v171
	v_add_u32_e32 v2, v0, v152
	s_movk_i32 s9, 0x1ff
	v_cmp_lt_u32_e32 vcc, s9, v2
	s_mov_b64 s[38:39], -1
	v_mov_b32_e32 v0, v170
	s_waitcnt lgkmcnt(0)
	v_mov_b32_e32 v1, v153
	s_and_saveexec_b64 s[36:37], vcc
	s_cbranch_execz .LBB0_886
	v_lshrrev_b32_e32 v0, 9, v2
	v_add_u32_e32 v3, 1, v0
	v_and_b32_e32 v2, 0xfffffe, v3
	s_mov_b64 s[38:39], 0
	v_mov_b32_e32 v4, v2
	v_mov_b32_e32 v5, v172
	v_mov_b64_e32 v[0:1], v[170:171]
